# attention tile staging: M0 written directly by the scalar adds, LDS base folded into one SGPR (four fewer scalar slots per staged tile)
# speedup vs baseline: 1.0070x; 1.0005x over previous
.LBB0_409:
	s_and_b64 vcc, exec, s[0:1]
	s_cbranch_vccz .LBB0_492
	v_readlane_b32 s0, v255, 12
	s_cmpk_gt_i32 s0, 0x7ff
	s_cbranch_scc1 .LBB0_492
	s_mov_b32 s24, m0
	v_readfirstlane_b32 s4, v198
	v_readlane_b32 s38, v255, 12
	s_lshr_b32 s27, s4, 6
	s_lshl_b32 s16, s27, 10
	s_add_i32 s8, s16, 0x8000
	s_nop 0
	s_lshr_b32 s2, s27, 2
	s_cmp_eq_u32 s2, 1
	s_cbranch_scc0 .Lat2_noprio
	s_setprio 1

.Lat2_unit_1:
	s_and_b32 s4, s38, 3
	s_lshl_b32 s4, s4, 1
	s_lshr_b32 s5, s26, 1
	s_add_i32 s4, s4, s5
	s_sub_i32 s5, 15, s4
	s_bitcmp1_b32 s26, 0
	s_cselect_b32 s4, s4, s5
	s_lshl_b32 s39, s4, 2
	s_add_i32 s39, s39, 4
	s_sub_i32 s18, s39, 4
	s_lshr_b32 s5, s38, 5
	s_lshl_b32 s5, s5, 12
	s_lshl_b32 s6, s4, 8
	s_add_i32 s6, s6, s5
	s_bfe_u32 s7, s38, 0x30002
	s_lshl_b32 s14, s6, 10
	s_lshl_b32 s15, s7, 7
	s_add_i32 s14, s14, s15
	s_add_u32 s72, s54, s14
	s_addc_u32 s73, s55, 0
	s_lshl_b32 s14, s5, 10
	s_add_i32 s15, s14, s15
	s_add_i32 s15, s15, 0x2000000
	s_add_u32 s74, s54, s15
	s_addc_u32 s75, s55, 0
	s_lshr_b32 s15, s7, 1
	s_lshl_b32 s15, s15, 8
	s_add_i32 s14, s14, s15
	s_add_u32 s76, s64, s14
	s_addc_u32 s77, s65, 0
	s_lshl_b32 s14, s6, 11
	s_lshl_b32 s15, s7, 8
	s_add_i32 s14, s14, s15
	s_add_u32 s78, s50, s14
	s_addc_u32 s79, s51, 0
	global_load_dwordx4 v[148:151], v225, s[72:73] offset:0
	global_load_dwordx4 v[152:155], v225, s[72:73] offset:32
	global_load_dwordx4 v[156:159], v225, s[72:73] offset:64
	global_load_dwordx4 v[160:163], v225, s[72:73] offset:96
	s_mov_b64 s[80:81], s[74:75]
	s_mov_b64 s[82:83], s[76:77]
	s_mov_b32 s59, 0
	s_mov_b32 s60, 0x2000
	s_mov_b32 s61, 0x4000
	s_mov_b32 s25, 0x6000
	s_add_i32 m0, s59, s16
	s_lshl_b32 s5, s59, 1
	global_load_lds_dwordx4 v200, s[80:81]
	s_add_i32 m0, s5, s8
	s_add_u32 s80, s80, 0x10000
	s_addc_u32 s81, s81, 0
	global_load_lds_dwordx4 v201, s[82:83]
	s_add_i32 m0, m0, 0x2000
	s_nop 0
	global_load_lds_dwordx4 v202, s[82:83]
	s_add_u32 s82, s82, 0x10000
	s_addc_u32 s83, s83, 0
	s_add_i32 m0, s60, s16
	s_lshl_b32 s5, s60, 1
	global_load_lds_dwordx4 v200, s[80:81]
	s_add_i32 m0, s5, s8
	s_add_u32 s80, s80, 0x10000
	s_addc_u32 s81, s81, 0
	global_load_lds_dwordx4 v201, s[82:83]
	s_add_i32 m0, m0, 0x2000
	s_nop 0
	global_load_lds_dwordx4 v202, s[82:83]
	s_add_u32 s82, s82, 0x10000
	s_addc_u32 s83, s83, 0
	s_add_i32 m0, s61, s16
	s_lshl_b32 s5, s61, 1
	global_load_lds_dwordx4 v200, s[80:81]
	s_add_i32 m0, s5, s8
	s_add_u32 s80, s80, 0x10000
	s_addc_u32 s81, s81, 0
	global_load_lds_dwordx4 v201, s[82:83]
	s_add_i32 m0, m0, 0x2000
	s_nop 0
	global_load_lds_dwordx4 v202, s[82:83]
	s_add_u32 s82, s82, 0x10000
	s_addc_u32 s83, s83, 0
	v_mov_b32_e32 v0, 0
	v_mov_b32_e32 v1, 0
	v_mov_b32_e32 v2, 0
	v_mov_b32_e32 v3, 0
	v_mov_b32_e32 v4, 0
	v_mov_b32_e32 v5, 0
	v_mov_b32_e32 v6, 0
	v_mov_b32_e32 v7, 0
	v_mov_b32_e32 v8, 0
	v_mov_b32_e32 v9, 0
	v_mov_b32_e32 v10, 0
	v_mov_b32_e32 v11, 0
	v_mov_b32_e32 v12, 0
	v_mov_b32_e32 v13, 0
	v_mov_b32_e32 v14, 0
	v_mov_b32_e32 v15, 0
	v_mov_b32_e32 v16, 0
	v_mov_b32_e32 v17, 0
	v_mov_b32_e32 v18, 0
	v_mov_b32_e32 v19, 0
	v_mov_b32_e32 v20, 0
	v_mov_b32_e32 v21, 0
	v_mov_b32_e32 v22, 0
	v_mov_b32_e32 v23, 0
	v_mov_b32_e32 v24, 0
	v_mov_b32_e32 v25, 0
	v_mov_b32_e32 v26, 0
	v_mov_b32_e32 v27, 0
	v_mov_b32_e32 v28, 0
	v_mov_b32_e32 v29, 0
	v_mov_b32_e32 v30, 0
	v_mov_b32_e32 v31, 0
	v_mov_b32_e32 v32, 0
	v_mov_b32_e32 v33, 0
	v_mov_b32_e32 v34, 0
	v_mov_b32_e32 v35, 0
	v_mov_b32_e32 v36, 0
	v_mov_b32_e32 v37, 0
	v_mov_b32_e32 v38, 0
	v_mov_b32_e32 v39, 0
	v_mov_b32_e32 v40, 0
	v_mov_b32_e32 v41, 0
	v_mov_b32_e32 v42, 0
	v_mov_b32_e32 v43, 0
	v_mov_b32_e32 v44, 0
	v_mov_b32_e32 v45, 0
	v_mov_b32_e32 v46, 0
	v_mov_b32_e32 v47, 0
	v_mov_b32_e32 v48, 0
	v_mov_b32_e32 v49, 0
	v_mov_b32_e32 v50, 0
	v_mov_b32_e32 v51, 0
	v_mov_b32_e32 v52, 0
	v_mov_b32_e32 v53, 0
	v_mov_b32_e32 v54, 0
	v_mov_b32_e32 v55, 0
	v_mov_b32_e32 v56, 0
	v_mov_b32_e32 v57, 0
	v_mov_b32_e32 v58, 0
	v_mov_b32_e32 v59, 0
	v_mov_b32_e32 v60, 0
	v_mov_b32_e32 v61, 0
	v_mov_b32_e32 v62, 0
	v_mov_b32_e32 v63, 0
	v_mov_b32_e32 v100, 0
	v_mov_b32_e32 v101, 0
	v_mov_b32_e32 v102, 0
	v_mov_b32_e32 v103, 0
	v_mov_b32_e32 v104, 0
	v_mov_b32_e32 v105, 0
	v_mov_b32_e32 v106, 0
	v_mov_b32_e32 v107, 0
	v_mov_b32_e32 v108, 0
	v_mov_b32_e32 v109, 0
	v_mov_b32_e32 v110, 0
	v_mov_b32_e32 v111, 0
	v_mov_b32_e32 v112, 0
	v_mov_b32_e32 v113, 0
	v_mov_b32_e32 v114, 0
	v_mov_b32_e32 v115, 0
	v_mov_b32_e32 v210, 0
	v_mov_b32_e32 v232, 0
	v_mov_b32_e32 v233, 0
	v_mov_b32_e32 v234, 0
	v_mov_b32_e32 v235, 0
	s_mov_b32 s62, 0xf149f2ca
	s_mov_b32 s47, 0xf149f2ca
	s_mov_b32 s45, 0
	s_waitcnt vmcnt(6)
	s_barrier
	s_cmp_lt_u32 s45, s18
	s_cbranch_scc0 .Lat2_band_3
.Lat2_main_2:
	v_add_u32_e32 v205, s59, v203
	ds_read_b128 v[116:119], v205 offset:0
	ds_read_b128 v[120:123], v205 offset:512
	ds_read_b128 v[124:127], v205 offset:2048
	ds_read_b128 v[128:131], v205 offset:2560
	ds_read_b128 v[132:135], v205 offset:4096
	ds_read_b128 v[136:139], v205 offset:4608
	ds_read_b128 v[140:143], v205 offset:6144
	ds_read_b128 v[144:147], v205 offset:6656
	s_nop 0
	s_add_i32 m0, s25, s16
	s_lshl_b32 s5, s25, 1
	global_load_lds_dwordx4 v200, s[80:81]
	s_add_i32 m0, s5, s8
	s_add_u32 s80, s80, 0x10000
	s_addc_u32 s81, s81, 0
	global_load_lds_dwordx4 v201, s[82:83]
	s_add_i32 m0, m0, 0x2000
	s_nop 0
	global_load_lds_dwordx4 v202, s[82:83]
	s_add_u32 s82, s82, 0x10000
	s_addc_u32 s83, s83, 0
	s_lshl_b32 s7, s59, 1
	v_add_u32_e32 v206, s7, v204
	s_waitcnt lgkmcnt(6)
	v_mfma_f32_32x32x16_bf16 v[64:79], v[116:119], v[148:151], v[100:115]
	v_mfma_f32_32x32x16_bf16 v[80:95], v[120:123], v[148:151], v[100:115]
	s_waitcnt lgkmcnt(4)
	v_mfma_f32_32x32x16_bf16 v[64:79], v[124:127], v[152:155], v[64:79]
	v_mfma_f32_32x32x16_bf16 v[80:95], v[128:131], v[152:155], v[80:95]
	s_waitcnt lgkmcnt(2)
	v_mfma_f32_32x32x16_bf16 v[64:79], v[132:135], v[156:159], v[64:79]
	v_mfma_f32_32x32x16_bf16 v[80:95], v[136:139], v[156:159], v[80:95]
	s_waitcnt lgkmcnt(0)
	v_mfma_f32_32x32x16_bf16 v[64:79], v[140:143], v[160:163], v[64:79]
	v_mfma_f32_32x32x16_bf16 v[80:95], v[144:147], v[160:163], v[80:95]
	ds_read_b64_tr_b16 v[164:165], v206 offset:0
	ds_read_b64_tr_b16 v[166:167], v206 offset:512
	ds_read_b64_tr_b16 v[168:169], v206 offset:4096
	ds_read_b64_tr_b16 v[170:171], v206 offset:4608
	ds_read_b64_tr_b16 v[172:173], v206 offset:8192
	ds_read_b64_tr_b16 v[174:175], v206 offset:8704
	ds_read_b64_tr_b16 v[176:177], v206 offset:12288
	ds_read_b64_tr_b16 v[178:179], v206 offset:12800
	ds_read_b64_tr_b16 v[180:181], v206 offset:1024
	ds_read_b64_tr_b16 v[182:183], v206 offset:1536
	ds_read_b64_tr_b16 v[184:185], v206 offset:5120
	ds_read_b64_tr_b16 v[186:187], v206 offset:5632
	ds_read_b64_tr_b16 v[188:189], v206 offset:9216
	ds_read_b64_tr_b16 v[190:191], v206 offset:9728
	ds_read_b64_tr_b16 v[192:193], v206 offset:13312
	ds_read_b64_tr_b16 v[194:195], v206 offset:13824
	v_max3_f32 v215, v64, v65, v80
	v_max3_f32 v216, v66, v67, v81
	v_max3_f32 v215, v215, v82, v83
	v_max3_f32 v216, v216, v68, v69
	v_max3_f32 v215, v215, v70, v71
	v_max3_f32 v216, v216, v84, v85
	v_max3_f32 v215, v215, v86, v87
	v_max3_f32 v216, v216, v72, v73
	v_max3_f32 v215, v215, v74, v75
	v_max3_f32 v216, v216, v88, v89
	v_max3_f32 v215, v215, v90, v91
	v_max3_f32 v216, v216, v76, v77
	v_max3_f32 v215, v215, v78, v79
	v_max3_f32 v216, v216, v92, v93
	v_max3_f32 v215, v215, v94, v95
	v_max_f32_e32 v214, v215, v216
	v_mov_b32_e32 v215, v214
	s_nop 1
	v_permlane32_swap_b32_e32 v214, v215
	s_nop 0
	v_max_f32_e32 v214, v214, v215
	v_cmp_lt_f32_e32 vcc, s62, v214
	s_cmp_lg_u64 vcc, 0
	s_cbranch_scc1 .Lat2_resc_7

.Lat2_band_3:
.Lat2_bandloop_4:
	s_sub_i32 s19, s45, s18
	s_add_i32 s6, s45, 3
	s_cmp_lt_u32 s6, s39
	s_cbranch_scc0 .Lat2_nodma_16
	s_add_i32 m0, s25, s16
	s_lshl_b32 s5, s25, 1
	global_load_lds_dwordx4 v200, s[80:81]
	s_add_i32 m0, s5, s8
	s_add_u32 s80, s80, 0x10000
	s_addc_u32 s81, s81, 0
	global_load_lds_dwordx4 v201, s[82:83]
	s_add_i32 m0, m0, 0x2000
	s_nop 0
	global_load_lds_dwordx4 v202, s[82:83]
	s_add_u32 s82, s82, 0x10000
	s_addc_u32 s83, s83, 0
